# attention phase: one static s_setprio 1 for waves 4-7 at phase entry (strategy 4), reset by the next GEMM phase
# speedup vs baseline: 1.0360x; 1.0055x over previous
; #define LAS __attribute__((address_space(3)))
; #define GRID_SYNC() xcd_barrier(xbar)
; __global__ void __launch_bounds__(512, 2) mega_fwd(Args a) {
;     ...
;         GRID_SYNC();
;         {
;             LAS unsigned* qw = (LAS unsigned*)(F.lds + att::L_QW); unsigned* qctr = ctl + 64 * (l + 1);
;             int idx = c;
;             while (idx < 1280) {
;                 unsigned nx;
;                 if (idx < 416 || idx >= 1184) {
;                     const int j = idx < 416 ? idx : idx - 1184 + 416, qb = 15 - (j >> 5), bh = j & 31, b = bh >> 3, h = bh & 7; const size_t rb = (size_t)b * SEQ;
;                     nx = att::attn_unit<1, 64>(PROJ + rb * PW + 1536 + h * 64, PROJ + rb * PW + 2048 + h * 64, PROJ + rb * PW + 2560 + h * 64, PW, PW, OB + (size_t)T * 512 + rb * 512 + h * 64, qb * 256, LOGF + (size_t)h * T + rb, lds, qctr);
;                 } else if (idx >= 672) {
;                     const int j = idx - 672, qb = 15 - (j >> 5), bh = j & 31, b = bh >> 3, h = bh & 7; const size_t rb = (size_t)b * SEQ;
;                     nx = att::attn_unit<0, 64>(PROJ + rb * PW + h * 64, PROJ + rb * PW + 512 + h * 64, PROJ + rb * PW + 1024 + h * 64, PW, PW, OB + rb * 512 + h * 64, qb * 256, nullptr, lds, qctr);
;                 } else {
;                     const int j = idx - 416, qb = j & 15, bhm = j >> 4, b = bhm >> 2, hm = bhm & 3; const size_t rb = (size_t)b * SEQ;
;                     const bf16_t* kv = KVMEM + (size_t)l * DM * DM + (size_t)b * MEML * DM + hm * 128;
.LBB0_449:
	s_or_b64 exec, exec, s[0:1]
	v_readlane_b32 s0, v255, 2
	v_readlane_b32 s1, v255, 3
	s_mov_b32 s1, s35
	s_lshl_b32 s34, s0, 6
	v_writelane_b32 v255, s0, 8
	v_readlane_b32 s4, v251, 1
	v_readlane_b32 s6, v251, 3
	v_writelane_b32 v255, s1, 9
	s_lshl_b64 s[0:1], s[34:35], 2
	v_readlane_b32 s7, v251, 4
	s_add_u32 s0, s6, s0
	s_addc_u32 s1, s7, s1
	v_writelane_b32 v255, s0, 10
	s_waitcnt lgkmcnt(0)
	s_barrier
	v_readfirstlane_b32 s2, v224
	s_cmp_lt_u32 s2, 0x100
	s_cbranch_scc1 .Latt_prio_skip
	s_setprio 1
.Latt_prio_skip:
	v_writelane_b32 v255, s1, 11
	v_readlane_b32 s0, v254, 60
	s_lshl_b32 s0, s0, 21
	v_readlane_b32 s1, v251, 60
	s_add_u32 s0, s1, s0
	v_writelane_b32 v255, s0, 12
	v_readlane_b32 s0, v251, 61
	s_addc_u32 s0, s0, 0
	s_nop 0
	v_writelane_b32 v255, s0, 13
	v_readlane_b32 s0, v251, 5
	s_mov_b32 s18, s0
	v_readlane_b32 s5, v251, 2
	v_readlane_b32 s1, v251, 6
	s_branch .LBB0_451
